# hl balance thresholds 120/320 instead of 86/230 (m3 queue items reserved for workgroups with fewer gates tiles)
# speedup vs baseline: 1.0042x; 1.0042x over previous
.LBB0_1227:
	s_or_b64 exec, exec, s[4:5]
	v_mov_b32_e32 v0, s59
	s_waitcnt lgkmcnt(0)
	s_barrier
	ds_read_b32 v0, v0
	s_mov_b64 s[4:5], -1
	s_waitcnt lgkmcnt(0)
	v_cmp_le_i32_e32 vcc, s37, v0
	v_readfirstlane_b32 s63, v0
	s_cbranch_vccnz .LBB0_1222
	s_mov_b32 s98, 0
	s_cmpk_lg_i32 s96, 0x100
	s_cbranch_scc1 .Lhl_set
	v_readlane_b32 s98, v255, 26
	s_cmp_eq_u32 s98, -1
	s_movk_i32 s98, 128
	s_cselect_b32 s98, 208, s98
	s_movk_i32 s99, 320
	s_cselect_b32 s99, 120, s99
	s_cmp_lt_i32 s2, s98
	s_cselect_b32 s98, 1, 0
	s_sub_i32 s99, s37, s99
	s_cmp_ge_i32 s63, s99
	s_cselect_b32 s99, 1, 0
	s_and_b32 s98, s98, s99
